# v108: v107 + per-tile advance of the LDS-DMA source addresses on the shared SGPR offset instead of two 64-bit VALU adds before the loop barrier
# baseline (speedup 1.0000x reference)
; #define ATT_WAITV(n) asm volatile("s_waitcnt vmcnt(" #n ")" ::: "memory")
; template <int MODE>
; __device__ __forceinline__ void attn_unit(const Params& P, LAS unsigned char* lds, const int b, const int h, const int qb) {
;     ...
;     for (int kt = kt0; kt < nt; ++kt) {
;         const int rel = kt - kt0, cur = rel & (AL_NBUF - 1);
;         if (kt + 2 < nt) { if (FOX) ATT_WAITV(10); else ATT_WAITV(8); } else if (kt + 1 < nt) { if (FOX) ATT_WAITV(5); else ATT_WAITV(4); } else ATT_WAITV(0);
;         __builtin_amdgcn_s_barrier(); asm volatile("" ::: "memory");
;         if (kt + AL_PD < nt) ATT_DMA(kt + AL_PD, (rel + AL_PD) & (AL_NBUF - 1));
.LBB0_474:
	s_add_i32 s40, s40, 1
	s_add_i32 s38, s38, 0x8000
	s_add_i32 s39, s39, 64
	v_subrev_u32_e32 v167, 64, v167
	s_add_u32 s68, s68, s30
	s_addc_u32 s69, s69, s31
	s_cmp_eq_u32 s22, s40
	s_cbranch_scc1 .LBB0_490
